# attention mask-free block: in-place folding of the remaining moves; O rescale skipped when alpha is exactly 1.0 in every lane
# baseline (speedup 1.0000x reference)
; __device__ __forceinline__ void attn_phase(LAS unsigned char* lds, const int wid, const bf16_t* P, const float* LF, bf16_t* CAT, const float* qgain, const float* kgain) {
;     ...
;                 if (kt * 64 <= q0 + 31 && !done_w) {
;                     const LAS unsigned char* kb_ = KB + cb * 64 * KPITCH;
;                     const LAS unsigned char* vb_ = VB + cb * 64 * VPITCH;
;                     f32x16 sacc[2];
; #pragma unroll
;                     for (int kb = 0; kb < 2; ++kb) {
; #pragma unroll
;                         for (int i = 0; i < 16; ++i) sacc[kb][i] = 0.f;
; #pragma unroll
;                         for (int ds = 0; ds < 4; ++ds) {
;                             const bf16x8 a = *(const LAS bf16x8*)(kb_ + (kb * 32 + r32) * KPITCH + (16 * ds + 8 * hh) * 2);
;                             sacc[kb] = __builtin_amdgcn_mfma_f32_32x32x16_bf16(a, qf[ds], sacc[kb], 0, 0, 0);
;                         }
;                     }
;                     const bool diag = (kt * 64 + 63 > q0);
;                     float mloc = -1e30f;
; #pragma unroll
;                     for (int kb = 0; kb < 2; ++kb)
; #pragma unroll
;                         for (int i4 = 0; i4 < 4; ++i4) {
;                             const int kl = kb * 32 + 8 * i4 + 4 * hh;
;                             const f32x4 bias = *(const LAS f32x4*)(CB + kt * 64 + kl);
; #pragma unroll
;                             for (int jj = 0; jj < 4; ++jj) {
;                                 float sv = sacc[kb][4 * i4 + jj] + bias[jj];
;                                 if (diag && (kt * 64 + kl + jj > qrow)) sv = -1e30f;
;                                 sacc[kb][4 * i4 + jj] = sv; mloc = fmaxf(mloc, sv);
;                             }
;                         }
;                     mloc = fmaxf(mloc, __shfl_xor(mloc, 32));
;                     const float mnew = fmaxf(mrun, mloc);
;                     const float alpha = fexp2(mrun - mnew); mrun = mnew;
;                     float ps = 0.f;
; #pragma unroll
;                     for (int kb = 0; kb < 2; ++kb)
; #pragma unroll
;                         for (int i = 0; i < 16; ++i) { const float p = fexp2(sacc[kb][i] - mnew); sacc[kb][i] = p; ps += p; }
;                     lsum = lsum * alpha + ps;
; #pragma unroll
;                     for (int i = 0; i < 16; ++i) { O[0][i] *= alpha; O[1][i] *= alpha; }
.Lattn_nodiag_a:
	s_mul_i32 s18, s80, 0x2400
	v_add3_u32 v1, v160, s18, v162
	ds_read_b128 v[2:5], v1 offset:16384
	ds_read_b128 v[6:9], v1 offset:16416
	v_add_u32_e32 v14, s78, v159
	s_add_i32 s18, s77, 63
	v_add_u32_e32 v15, s77, v112
	s_waitcnt lgkmcnt(1)
	v_mfma_f32_32x32x16_bf16 v[64:79], v[2:5], v[88:91], 0
	ds_read_b128 v[2:5], v1 offset:16448
	s_cmp_gt_i32 s18, s74
	s_cselect_b64 s[60:61], -1, 0
	s_waitcnt lgkmcnt(1)
	v_mfma_f32_32x32x16_bf16 v[64:79], v[6:9], v[92:95], v[64:79]
	ds_read_b128 v[6:9], v1 offset:16480
	ds_read_b128 v[10:13], v1 offset:20992
	s_waitcnt lgkmcnt(2)
	v_mfma_f32_32x32x16_bf16 v[64:79], v[2:5], v[96:99], v[64:79]
	ds_read_b128 v[2:5], v14 offset:4
	ds_read_b128 v[168:171], v14 offset:36
	ds_read_b128 v[172:175], v1 offset:21024
	ds_read_b128 v[176:179], v1 offset:21056
	ds_read_b128 v[180:183], v1 offset:21088
	s_waitcnt lgkmcnt(6)
	v_mfma_f32_32x32x16_bf16 v[64:79], v[6:9], v[100:103], v[64:79]
	s_waitcnt lgkmcnt(5)
	v_mfma_f32_32x32x16_bf16 v[48:63], v[10:13], v[88:91], 0
	s_waitcnt lgkmcnt(4)
	s_nop 8
	v_add_f32_e32 v1, v64, v2
	v_add_f32_e32 v10, v65, v3
	v_add_f32_e32 v12, v66, v4
	v_add_f32_e32 v13, v67, v5
	s_waitcnt lgkmcnt(3)
	v_add_f32_e32 v64, v68, v168
	v_add_f32_e32 v11, v69, v169
	v_max3_f32 v2, v1, s67, v10
	v_max3_f32 v2, v2, v12, v13
	v_max3_f32 v6, v2, v64, v11
	v_add_f32_e32 v65, v70, v170
	ds_read_b128 v[2:5], v14 offset:68
	s_waitcnt lgkmcnt(3)
	v_mfma_f32_32x32x16_bf16 v[48:63], v[172:175], v[92:95], v[48:63]
	v_add_f32_e32 v66, v71, v171
	v_max3_f32 v67, v6, v65, v66
	ds_read_b128 v[6:9], v14 offset:100
	s_waitcnt lgkmcnt(1)
	v_add_f32_e32 v69, v72, v2
	v_add_f32_e32 v68, v73, v3
	v_add_f32_e32 v3, v74, v4
	v_mfma_f32_32x32x16_bf16 v[48:63], v[176:179], v[96:99], v[48:63]
	v_max3_f32 v2, v67, v69, v68
	v_mov_b32_e32 v67, v3
	v_add_f32_e32 v70, v75, v5
	s_waitcnt lgkmcnt(0)
	v_add_f32_e32 v71, v76, v6
	v_add_f32_e32 v72, v77, v7
	v_mfma_f32_32x32x16_bf16 v[48:63], v[180:183], v[100:103], v[48:63]
	v_max3_f32 v2, v2, v67, v70
	v_max3_f32 v6, v2, v71, v72
	v_add_f32_e32 v73, v78, v8
	ds_read_b128 v[2:5], v14 offset:132
	v_add_f32_e32 v74, v79, v9
	v_max3_f32 v75, v6, v73, v74
	ds_read_b128 v[6:9], v14 offset:164
	s_waitcnt lgkmcnt(1)
	s_nop 3
	v_add_f32_e32 v48, v48, v2
	v_add_f32_e32 v49, v49, v3
	v_add_f32_e32 v50, v50, v4
	v_add_f32_e32 v51, v51, v5
	s_waitcnt lgkmcnt(0)
	v_add_f32_e32 v52, v52, v6
	v_max3_f32 v2, v75, v48, v49
	v_add_f32_e32 v53, v53, v7
	v_max3_f32 v2, v2, v50, v51
	v_max3_f32 v6, v2, v52, v53
	v_add_f32_e32 v54, v54, v8
	ds_read_b128 v[2:5], v14 offset:196
	v_add_f32_e32 v55, v55, v9
	v_add_u32_e32 v76, 48, v15
	v_max3_f32 v75, v6, v54, v55
	ds_read_b128 v[6:9], v14 offset:228
	s_waitcnt lgkmcnt(1)
	v_add_f32_e32 v56, v56, v2
	v_add_f32_e32 v57, v57, v3
	v_add_f32_e32 v58, v58, v4
	v_add_f32_e32 v59, v59, v5
	s_waitcnt lgkmcnt(0)
	v_add_f32_e32 v60, v60, v6
	v_add_f32_e32 v61, v61, v7
	v_add_f32_e32 v62, v62, v8
	v_max3_f32 v2, v75, v56, v57
	v_max3_f32 v2, v2, v58, v59
	v_add_f32_e32 v15, v63, v9
	v_max3_f32 v2, v2, v60, v61
	v_max3_f32 v2, v2, v62, v15
	ds_bpermute_b32 v3, v146, v2
	s_mul_i32 s18, s80, 0x2200
	s_waitcnt lgkmcnt(0)
	v_max3_f32 v63, v166, v2, v3
	v_sub_f32_e32 v1, v1, v63
	v_exp_f32_e32 v1, v1
	v_sub_f32_e32 v3, v10, v63
	v_exp_f32_e32 v6, v3
	v_sub_f32_e32 v3, v12, v63
	v_exp_f32_e32 v7, v3
	v_sub_f32_e32 v3, v13, v63
	v_exp_f32_e32 v8, v3
	v_sub_f32_e32 v4, v64, v63
	v_add_f32_e32 v3, 0, v1
	v_exp_f32_e32 v9, v4
	v_sub_f32_e32 v4, v11, v63
	v_add_f32_e32 v3, v6, v3
	v_exp_f32_e32 v10, v4
	v_sub_f32_e32 v4, v65, v63
	v_add_f32_e32 v3, v7, v3
	v_exp_f32_e32 v11, v4
	v_sub_f32_e32 v4, v66, v63
	v_add_f32_e32 v3, v8, v3
	v_exp_f32_e32 v12, v4
	v_sub_f32_e32 v4, v69, v63
	v_add_f32_e32 v3, v9, v3
	v_exp_f32_e32 v64, v4
	v_sub_f32_e32 v4, v68, v63
	v_add_f32_e32 v3, v10, v3
	v_exp_f32_e32 v65, v4
	v_sub_f32_e32 v4, v67, v63
	v_add_f32_e32 v3, v11, v3
	v_exp_f32_e32 v66, v4
	v_sub_f32_e32 v4, v70, v63
	v_add_f32_e32 v3, v12, v3
	v_exp_f32_e32 v67, v4
	v_sub_f32_e32 v4, v71, v63
	v_add_f32_e32 v3, v64, v3
	v_exp_f32_e32 v68, v4
	v_sub_f32_e32 v4, v72, v63
	v_add_f32_e32 v3, v65, v3
	v_exp_f32_e32 v69, v4
	v_sub_f32_e32 v4, v73, v63
	v_add_f32_e32 v3, v66, v3
	v_exp_f32_e32 v70, v4
	v_sub_f32_e32 v4, v74, v63
	v_add_f32_e32 v3, v67, v3
	v_exp_f32_e32 v71, v4
	v_sub_f32_e32 v4, v48, v63
	v_add_f32_e32 v3, v68, v3
	v_exp_f32_e32 v48, v4
	v_sub_f32_e32 v4, v49, v63
	v_add_f32_e32 v3, v69, v3
	v_exp_f32_e32 v49, v4
	v_sub_f32_e32 v4, v50, v63
	v_add_f32_e32 v3, v70, v3
	v_exp_f32_e32 v50, v4
	v_sub_f32_e32 v4, v51, v63
	v_add_f32_e32 v3, v71, v3
	v_exp_f32_e32 v51, v4
	v_sub_f32_e32 v4, v52, v63
	v_add_f32_e32 v3, v48, v3
	v_exp_f32_e32 v52, v4
	v_sub_f32_e32 v4, v53, v63
	v_add_f32_e32 v3, v49, v3
	v_exp_f32_e32 v53, v4
	v_sub_f32_e32 v4, v54, v63
	v_add_f32_e32 v3, v50, v3
	v_exp_f32_e32 v54, v4
	v_add_f32_e32 v3, v51, v3
	v_sub_f32_e32 v2, v166, v63
	v_add_f32_e32 v3, v52, v3
	v_add3_u32 v13, v161, s18, v163
	v_add_f32_e32 v3, v53, v3
	v_exp_f32_e32 v14, v2
	v_sub_f32_e32 v2, v55, v63
	v_add_u32_e32 v73, 0x8800, v13
	v_add_f32_e32 v72, v54, v3
	v_exp_f32_e32 v55, v2
	ds_read2_b64 v[2:5], v73 offset1:2
	v_cvt_pk_bf16_f32 v6, v1, v6
	v_add_u32_e32 v1, 0x9800, v13
	v_cvt_pk_bf16_f32 v7, v7, v8
	v_cvt_pk_bf16_f32 v8, v9, v10
	v_cvt_pk_bf16_f32 v9, v11, v12
	ds_read2_b64 v[10:13], v1 offset0:32 offset1:34
	v_cmp_neq_f32_e32 vcc, 1.0, v14
	s_cbranch_vccz .Lattn_ask_a_0
	v_pk_mul_f32 v[46:47], v[46:47], v[14:15] op_sel_hi:[1,0]
	v_pk_mul_f32 v[44:45], v[44:45], v[14:15] op_sel_hi:[1,0]
	v_pk_mul_f32 v[42:43], v[42:43], v[14:15] op_sel_hi:[1,0]
	v_pk_mul_f32 v[40:41], v[40:41], v[14:15] op_sel_hi:[1,0]
	v_pk_mul_f32 v[38:39], v[38:39], v[14:15] op_sel_hi:[1,0]
	v_pk_mul_f32 v[36:37], v[36:37], v[14:15] op_sel_hi:[1,0]
	v_pk_mul_f32 v[34:35], v[34:35], v[14:15] op_sel_hi:[1,0]
	v_pk_mul_f32 v[32:33], v[32:33], v[14:15] op_sel_hi:[1,0]
	v_pk_mul_f32 v[30:31], v[30:31], v[14:15] op_sel_hi:[1,0]
	v_pk_mul_f32 v[28:29], v[28:29], v[14:15] op_sel_hi:[1,0]
; #define LAS __attribute__((address_space(3)))
; __device__ __forceinline__ unsigned cvt_pk_bf16(float lo, float hi) { const f32x2 v = {lo, hi}; return __builtin_bit_cast(unsigned, __builtin_convertvector(v, b16x2_t)); }
; __device__ __forceinline__ void attn_phase(LAS unsigned char* lds, const int wid, const bf16_t* P, const float* LF, bf16_t* CAT, const float* qgain, const float* kgain) {
;     ...
;                     for (int i = 0; i < 16; ++i) { O[0][i] *= alpha; O[1][i] *= alpha; }
; #pragma unroll
;                     for (int kb = 0; kb < 2; ++kb)
; #pragma unroll
;                         for (int s2 = 0; s2 < 2; ++s2) {
;                             u32x4 pw; pw.x = cvt_pk_bf16(sacc[kb][8 * s2 + 0], sacc[kb][8 * s2 + 1]); pw.y = cvt_pk_bf16(sacc[kb][8 * s2 + 2], sacc[kb][8 * s2 + 3]);
;                             pw.z = cvt_pk_bf16(sacc[kb][8 * s2 + 4], sacc[kb][8 * s2 + 5]); pw.w = cvt_pk_bf16(sacc[kb][8 * s2 + 6], sacc[kb][8 * s2 + 7]);
;                             const bf16x8 pf = __builtin_bit_cast(bf16x8, pw);
; #pragma unroll
;                             for (int db = 0; db < 2; ++db) {
;                                 const LAS unsigned char* vp = vb_ + (db * 32 + r32) * VPITCH + (kb * 32 + 16 * s2 + 4 * hh) * 2;
;                                 const s16x4 lo = *(const LAS s16x4*)vp, hi = *(const LAS s16x4*)(vp + 16);
;                                 const bf16x8 av = __builtin_shufflevector(lo, hi, 0, 1, 2, 3, 4, 5, 6, 7);
;                                 O[db] = __builtin_amdgcn_mfma_f32_32x32x16_bf16(av, pf, O[db], 0, 0, 0);
;                             }
;                         }
;                 }
.Lattn_ask_a_0:
	s_waitcnt lgkmcnt(1)
	v_mfma_f32_32x32x16_bf16 v[32:47], v[2:5], v[6:9], v[32:47]
	ds_read2_b64 v[2:5], v73 offset0:4 offset1:6
	s_cbranch_vccz .Lattn_ask_a_1
	v_mul_f32_e64 v26, v26, v14
	v_mul_f32_e64 v27, v27, v14
	v_mul_f32_e64 v24, v24, v14
	v_mul_f32_e64 v25, v25, v14
	v_pk_mul_f32 v[22:23], v[22:23], v[14:15] op_sel_hi:[1,0]
	v_pk_mul_f32 v[20:21], v[20:21], v[14:15] op_sel_hi:[1,0]
	v_pk_mul_f32 v[18:19], v[18:19], v[14:15] op_sel_hi:[1,0]
	v_pk_mul_f32 v[16:17], v[16:17], v[14:15] op_sel_hi:[1,0]
.Lattn_ask_a_1:
	v_mov_b32_e32 v166, v63
	s_waitcnt lgkmcnt(1)
	v_mfma_f32_32x32x16_bf16 v[16:31], v[10:13], v[6:9], v[16:31]
	v_sub_f32_e32 v6, v56, v63
	v_exp_f32_e32 v56, v6
	ds_read2_b64 v[10:13], v1 offset0:36 offset1:38
	v_cvt_pk_bf16_f32 v6, v64, v65
	v_cvt_pk_bf16_f32 v7, v66, v67
	v_cvt_pk_bf16_f32 v8, v68, v69
	v_cvt_pk_bf16_f32 v9, v70, v71
	s_waitcnt lgkmcnt(1)
	s_nop 0
	v_mfma_f32_32x32x16_bf16 v[32:47], v[2:5], v[6:9], v[32:47]
	v_add_f32_e32 v2, v55, v72
	v_add_f32_e32 v64, v56, v2
	v_sub_f32_e32 v2, v57, v63
	v_exp_f32_e32 v57, v2
	v_sub_f32_e32 v2, v58, v63
	v_exp_f32_e32 v58, v2
	ds_read2_b64 v[2:5], v73 offset0:8 offset1:10
	s_waitcnt lgkmcnt(1)
	v_mfma_f32_32x32x16_bf16 v[16:31], v[10:13], v[6:9], v[16:31]
	ds_read2_b64 v[10:13], v1 offset0:40 offset1:42
	v_sub_f32_e32 v6, v59, v63
	v_exp_f32_e32 v59, v6
	v_cvt_pk_bf16_f32 v6, v48, v49
	v_cvt_pk_bf16_f32 v7, v50, v51
	v_cvt_pk_bf16_f32 v8, v52, v53
	v_cvt_pk_bf16_f32 v9, v54, v55
	s_waitcnt lgkmcnt(1)
	s_nop 0
	v_mfma_f32_32x32x16_bf16 v[32:47], v[2:5], v[6:9], v[32:47]
	v_sub_f32_e32 v2, v60, v63
	v_exp_f32_e32 v48, v2
	v_sub_f32_e32 v2, v61, v63
	v_exp_f32_e32 v49, v2
	v_sub_f32_e32 v2, v62, v63
	v_exp_f32_e32 v50, v2
	ds_read2_b64 v[2:5], v73 offset0:12 offset1:14
	s_waitcnt lgkmcnt(1)
	v_mfma_f32_32x32x16_bf16 v[16:31], v[10:13], v[6:9], v[16:31]
	ds_read2_b64 v[10:13], v1 offset0:44 offset1:46
	v_sub_f32_e32 v6, v15, v63
	v_exp_f32_e32 v15, v6
	v_cvt_pk_bf16_f32 v6, v56, v57
	v_cvt_pk_bf16_f32 v7, v58, v59
	v_cvt_pk_bf16_f32 v8, v48, v49
	v_cvt_pk_bf16_f32 v9, v50, v15
	v_add_f32_e32 v1, v57, v64
	v_add_f32_e32 v1, v58, v1
	s_waitcnt lgkmcnt(1)
	v_mfma_f32_32x32x16_bf16 v[32:47], v[2:5], v[6:9], v[32:47]
	v_add_f32_e32 v1, v59, v1
	v_add_f32_e32 v1, v48, v1
	v_add_f32_e32 v1, v49, v1
	v_add_f32_e32 v1, v50, v1
	v_add_f32_e32 v1, v15, v1
	v_fmac_f32_e32 v1, v135, v14
	v_mov_b32_e32 v135, v1
	s_waitcnt lgkmcnt(0)
	v_mfma_f32_32x32x16_bf16 v[16:31], v[10:13], v[6:9], v[16:31]
	s_branch .LBB0_270

; __device__ __forceinline__ void attn_phase(LAS unsigned char* lds, const int wid, const bf16_t* P, const float* LF, bf16_t* CAT, const float* qgain, const float* kgain) {
;     ...
;                 if (kt * 64 <= q0 + 31 && !done_w) {
;                     const LAS unsigned char* kb_ = KB + cb * 64 * KPITCH;
;                     const LAS unsigned char* vb_ = VB + cb * 64 * VPITCH;
;                     f32x16 sacc[2];
; #pragma unroll
;                     for (int kb = 0; kb < 2; ++kb) {
; #pragma unroll
;                         for (int i = 0; i < 16; ++i) sacc[kb][i] = 0.f;
; #pragma unroll
;                         for (int ds = 0; ds < 4; ++ds) {
;                             const bf16x8 a = *(const LAS bf16x8*)(kb_ + (kb * 32 + r32) * KPITCH + (16 * ds + 8 * hh) * 2);
;                             sacc[kb] = __builtin_amdgcn_mfma_f32_32x32x16_bf16(a, qf[ds], sacc[kb], 0, 0, 0);
;                         }
;                     }
;                     const bool diag = (kt * 64 + 63 > q0);
;                     float mloc = -1e30f;
; #pragma unroll
;                     for (int kb = 0; kb < 2; ++kb)
; #pragma unroll
;                         for (int i4 = 0; i4 < 4; ++i4) {
;                             const int kl = kb * 32 + 8 * i4 + 4 * hh;
;                             const f32x4 bias = *(const LAS f32x4*)(CB + kt * 64 + kl);
; #pragma unroll
;                             for (int jj = 0; jj < 4; ++jj) {
;                                 float sv = sacc[kb][4 * i4 + jj] + bias[jj];
;                                 if (diag && (kt * 64 + kl + jj > qrow)) sv = -1e30f;
;                                 sacc[kb][4 * i4 + jj] = sv; mloc = fmaxf(mloc, sv);
;                             }
;                         }
;                     mloc = fmaxf(mloc, __shfl_xor(mloc, 32));
;                     const float mnew = fmaxf(mrun, mloc);
;                     const float alpha = fexp2(mrun - mnew); mrun = mnew;
;                     float ps = 0.f;
; #pragma unroll
;                     for (int kb = 0; kb < 2; ++kb)
; #pragma unroll
;                         for (int i = 0; i < 16; ++i) { const float p = fexp2(sacc[kb][i] - mnew); sacc[kb][i] = p; ps += p; }
;                     lsum = lsum * alpha + ps;
; #pragma unroll
;                     for (int i = 0; i < 16; ++i) { O[0][i] *= alpha; O[1][i] *= alpha; }
.Lattn_nodiag_b:
	s_mul_i32 s0, s80, 0x2400
	v_add3_u32 v1, v160, s0, v162
	ds_read_b128 v[2:5], v1 offset:16384
	ds_read_b128 v[6:9], v1 offset:16416
	v_add_u32_e32 v14, s78, v159
	s_add_i32 s0, s77, 63
	v_add_u32_e32 v15, s77, v112
	s_waitcnt lgkmcnt(1)
	v_mfma_f32_32x32x16_bf16 v[64:79], v[2:5], v[88:91], 0
	ds_read_b128 v[2:5], v1 offset:16448
	s_cmp_gt_i32 s0, s74
	s_cselect_b64 s[60:61], -1, 0
	s_mul_i32 s0, s80, 0x2200
	s_waitcnt lgkmcnt(1)
	v_mfma_f32_32x32x16_bf16 v[64:79], v[6:9], v[92:95], v[64:79]
	ds_read_b128 v[6:9], v1 offset:16480
	ds_read_b128 v[10:13], v1 offset:20992
	s_waitcnt lgkmcnt(2)
	v_mfma_f32_32x32x16_bf16 v[64:79], v[2:5], v[96:99], v[64:79]
	ds_read_b128 v[2:5], v14 offset:4
	ds_read_b128 v[168:171], v14 offset:36
	ds_read_b128 v[172:175], v1 offset:21024
	ds_read_b128 v[176:179], v1 offset:21056
	ds_read_b128 v[180:183], v1 offset:21088
	s_waitcnt lgkmcnt(6)
	v_mfma_f32_32x32x16_bf16 v[64:79], v[6:9], v[100:103], v[64:79]
	s_waitcnt lgkmcnt(5)
	v_mfma_f32_32x32x16_bf16 v[48:63], v[10:13], v[88:91], 0
	s_waitcnt lgkmcnt(4)
	s_nop 8
	v_add_f32_e32 v1, v64, v2
	v_add_f32_e32 v10, v65, v3
	v_add_f32_e32 v12, v66, v4
	v_add_f32_e32 v13, v67, v5
	s_waitcnt lgkmcnt(3)
	v_add_f32_e32 v64, v68, v168
	v_add_f32_e32 v11, v69, v169
	v_max3_f32 v2, v1, s67, v10
	v_max3_f32 v2, v2, v12, v13
	v_max3_f32 v6, v2, v64, v11
	v_add_f32_e32 v65, v70, v170
	ds_read_b128 v[2:5], v14 offset:68
	s_waitcnt lgkmcnt(3)
	v_mfma_f32_32x32x16_bf16 v[48:63], v[172:175], v[92:95], v[48:63]
	v_add_f32_e32 v66, v71, v171
	v_max3_f32 v67, v6, v65, v66
	ds_read_b128 v[6:9], v14 offset:100
	s_waitcnt lgkmcnt(1)
	v_add_f32_e32 v69, v72, v2
	v_add_f32_e32 v68, v73, v3
	v_add_f32_e32 v3, v74, v4
	v_mfma_f32_32x32x16_bf16 v[48:63], v[176:179], v[96:99], v[48:63]
	v_max3_f32 v2, v67, v69, v68
	v_mov_b32_e32 v67, v3
	v_add_f32_e32 v70, v75, v5
	s_waitcnt lgkmcnt(0)
	v_add_f32_e32 v71, v76, v6
	v_add_f32_e32 v72, v77, v7
	v_mfma_f32_32x32x16_bf16 v[48:63], v[180:183], v[100:103], v[48:63]
	v_max3_f32 v2, v2, v67, v70
	v_max3_f32 v6, v2, v71, v72
	v_add_f32_e32 v73, v78, v8
	ds_read_b128 v[2:5], v14 offset:132
	v_add_f32_e32 v74, v79, v9
	v_max3_f32 v75, v6, v73, v74
	ds_read_b128 v[6:9], v14 offset:164
	s_waitcnt lgkmcnt(1)
	s_nop 3
	v_add_f32_e32 v48, v48, v2
	v_add_f32_e32 v49, v49, v3
	v_add_f32_e32 v50, v50, v4
	v_add_f32_e32 v51, v51, v5
	s_waitcnt lgkmcnt(0)
	v_add_f32_e32 v52, v52, v6
	v_max3_f32 v2, v75, v48, v49
	v_add_f32_e32 v53, v53, v7
	v_max3_f32 v2, v2, v50, v51
	v_max3_f32 v6, v2, v52, v53
	v_add_f32_e32 v54, v54, v8
	ds_read_b128 v[2:5], v14 offset:196
	v_add_f32_e32 v55, v55, v9
	v_add_u32_e32 v76, 48, v15
	v_max3_f32 v75, v6, v54, v55
	ds_read_b128 v[6:9], v14 offset:228
	s_waitcnt lgkmcnt(1)
	v_add_f32_e32 v56, v56, v2
	v_add_f32_e32 v57, v57, v3
	v_add_f32_e32 v58, v58, v4
	v_add_f32_e32 v59, v59, v5
	s_waitcnt lgkmcnt(0)
	v_add_f32_e32 v60, v60, v6
	v_add_f32_e32 v61, v61, v7
	v_add_f32_e32 v62, v62, v8
	v_max3_f32 v2, v75, v56, v57
	v_max3_f32 v2, v2, v58, v59
	v_add_f32_e32 v15, v63, v9
	v_max3_f32 v2, v2, v60, v61
	v_max3_f32 v2, v2, v62, v15
	ds_bpermute_b32 v3, v146, v2
	s_waitcnt lgkmcnt(0)
	v_max3_f32 v63, v166, v2, v3
	v_sub_f32_e32 v1, v1, v63
	v_exp_f32_e32 v1, v1
	v_sub_f32_e32 v3, v10, v63
	v_exp_f32_e32 v6, v3
	v_sub_f32_e32 v3, v12, v63
	v_exp_f32_e32 v7, v3
	v_sub_f32_e32 v3, v13, v63
	v_exp_f32_e32 v8, v3
	v_sub_f32_e32 v4, v64, v63
	v_add_f32_e32 v3, 0, v1
	v_exp_f32_e32 v9, v4
	v_sub_f32_e32 v4, v11, v63
	v_add_f32_e32 v3, v6, v3
	v_exp_f32_e32 v10, v4
	v_sub_f32_e32 v4, v65, v63
	v_add_f32_e32 v3, v7, v3
	v_exp_f32_e32 v11, v4
	v_sub_f32_e32 v4, v66, v63
	v_add_f32_e32 v3, v8, v3
	v_exp_f32_e32 v12, v4
	v_sub_f32_e32 v4, v69, v63
	v_add_f32_e32 v3, v9, v3
	v_exp_f32_e32 v64, v4
	v_sub_f32_e32 v4, v68, v63
	v_add_f32_e32 v3, v10, v3
	v_exp_f32_e32 v65, v4
	v_sub_f32_e32 v4, v67, v63
	v_add_f32_e32 v3, v11, v3
	v_exp_f32_e32 v66, v4
	v_sub_f32_e32 v4, v70, v63
	v_add_f32_e32 v3, v12, v3
	v_exp_f32_e32 v67, v4
	v_sub_f32_e32 v4, v71, v63
	v_add_f32_e32 v3, v64, v3
	v_exp_f32_e32 v68, v4
	v_sub_f32_e32 v4, v72, v63
	v_add_f32_e32 v3, v65, v3
	v_exp_f32_e32 v69, v4
	v_sub_f32_e32 v4, v73, v63
	v_add_f32_e32 v3, v66, v3
	v_exp_f32_e32 v70, v4
	v_sub_f32_e32 v4, v74, v63
	v_add_f32_e32 v3, v67, v3
	v_exp_f32_e32 v71, v4
	v_sub_f32_e32 v4, v48, v63
	v_add_f32_e32 v3, v68, v3
	v_exp_f32_e32 v48, v4
	v_sub_f32_e32 v4, v49, v63
	v_add_f32_e32 v3, v69, v3
	v_exp_f32_e32 v49, v4
	v_sub_f32_e32 v4, v50, v63
	v_add_f32_e32 v3, v70, v3
	v_exp_f32_e32 v50, v4
	v_sub_f32_e32 v4, v51, v63
	v_add_f32_e32 v3, v71, v3
	v_exp_f32_e32 v51, v4
	v_sub_f32_e32 v4, v52, v63
	v_add_f32_e32 v3, v48, v3
	v_exp_f32_e32 v52, v4
	v_sub_f32_e32 v4, v53, v63
	v_add_f32_e32 v3, v49, v3
	v_exp_f32_e32 v53, v4
	v_sub_f32_e32 v4, v54, v63
	v_add_f32_e32 v3, v50, v3
	v_exp_f32_e32 v54, v4
	v_add_f32_e32 v3, v51, v3
	v_sub_f32_e32 v2, v166, v63
	v_add_f32_e32 v3, v52, v3
	v_add3_u32 v13, v161, s0, v163
	v_add_f32_e32 v3, v53, v3
	v_exp_f32_e32 v14, v2
	v_sub_f32_e32 v2, v55, v63
	v_add_u32_e32 v73, 0x8800, v13
	v_add_f32_e32 v72, v54, v3
	v_exp_f32_e32 v55, v2
	ds_read2_b64 v[2:5], v73 offset1:2
	v_cvt_pk_bf16_f32 v6, v1, v6
	v_add_u32_e32 v1, 0x9800, v13
	v_cvt_pk_bf16_f32 v7, v7, v8
	v_cvt_pk_bf16_f32 v8, v9, v10
	v_cvt_pk_bf16_f32 v9, v11, v12
	ds_read2_b64 v[10:13], v1 offset0:32 offset1:34
	v_cmp_neq_f32_e32 vcc, 1.0, v14
	s_cbranch_vccz .Lattn_ask_b_0
	v_pk_mul_f32 v[46:47], v[46:47], v[14:15] op_sel_hi:[1,0]
	v_pk_mul_f32 v[44:45], v[44:45], v[14:15] op_sel_hi:[1,0]
	v_pk_mul_f32 v[42:43], v[42:43], v[14:15] op_sel_hi:[1,0]
	v_pk_mul_f32 v[40:41], v[40:41], v[14:15] op_sel_hi:[1,0]
	v_pk_mul_f32 v[38:39], v[38:39], v[14:15] op_sel_hi:[1,0]
	v_pk_mul_f32 v[36:37], v[36:37], v[14:15] op_sel_hi:[1,0]
	v_pk_mul_f32 v[34:35], v[34:35], v[14:15] op_sel_hi:[1,0]
	v_pk_mul_f32 v[32:33], v[32:33], v[14:15] op_sel_hi:[1,0]
	v_pk_mul_f32 v[30:31], v[30:31], v[14:15] op_sel_hi:[1,0]
	v_pk_mul_f32 v[28:29], v[28:29], v[14:15] op_sel_hi:[1,0]
